# v19 + rope-table loop with its position loads issued together, and the S5 W1 block written with 16-byte stores
# speedup vs baseline: 1.1706x; 1.0036x over previous
; __device__ __forceinline__ unsigned pk2(float lo, float hi) { return f2bf(lo) | (f2bf(hi) << 16); }
; __global__ void __launch_bounds__(NWAVES * 64, 2) fwd_kernel(Args args) {
;     ...
;             for (int i2 = tid; i2 < 128 * 128; i2 += 512) { const int row = i2 >> 7, c0 = (i2 & 127) * 2, n = row & 63; float v[2];
; #pragma unroll
;                 for (int e = 0; e < 2; ++e) { const int col = c0 + e, tau = col >> 4, p = col & 15;
;                     const float ar = ap[((15 - tau) * 64 + n) * 2], ai = ap[((15 - tau) * 64 + n) * 2 + 1], br = bb[(n * 16 + p) * 2], bi = bb[(n * 16 + p) * 2 + 1];
;                     v[e] = (row < 64) ? (ar * br - ai * bi) : (ar * bi + ai * br); }
;                 *(unsigned*)(W1 + (size_t)row * 256 + c0) = pk2(v[0], v[1]); }
.LBB0_56:
	s_or_b64 exec, exec, s[36:37]
	s_and_b32 s72, s24, 63
	s_lshl_b32 s72, s72, 17
	s_add_u32 s72, s72, 0x400000
	s_sub_u32 s76, s28, s72
	s_subb_u32 s77, s29, 0
	v_and_b32_e32 v144, 31, v38
	v_lshrrev_b32_e32 v145, 5, v38
	v_lshrrev_b32_e32 v146, 1, v144
	v_sub_u32_e32 v146, 15, v146
	v_and_b32_e32 v147, 1, v144
	v_lshlrev_b32_e32 v147, 6, v147
	v_lshlrev_b32_e32 v148, 3, v145
	v_lshl_add_u32 v148, v146, 9, v148
	v_lshl_add_u32 v149, v145, 7, v147
	v_lshlrev_b32_e32 v150, 4, v144
	v_lshl_add_u32 v150, v145, 9, v150
	ds_read_b64 v[152:153], v148 offset:0
	ds_read_b128 v[154:157], v149 offset:8704
	ds_read_b128 v[158:161], v149 offset:8720
	ds_read_b128 v[162:165], v149 offset:8736
	ds_read_b128 v[166:169], v149 offset:8752
	s_waitcnt lgkmcnt(0)
	v_mul_f32_e32 v172, v153, v155
	v_fma_f32 v180, v152, v154, -v172
	v_mul_f32_e32 v174, v153, v157
	v_fma_f32 v181, v152, v156, -v174
	v_mul_f32_e32 v172, v153, v159
	v_fma_f32 v182, v152, v158, -v172
	v_mul_f32_e32 v174, v153, v161
	v_fma_f32 v183, v152, v160, -v174
	v_mul_f32_e32 v172, v153, v163
	v_fma_f32 v184, v152, v162, -v172
	v_mul_f32_e32 v174, v153, v165
	v_fma_f32 v185, v152, v164, -v174
	v_mul_f32_e32 v172, v153, v167
	v_fma_f32 v186, v152, v166, -v172
	v_mul_f32_e32 v174, v153, v169
	v_fma_f32 v187, v152, v168, -v174
	v_cvt_pk_bf16_f32 v190, v180, v181
	v_cvt_pk_bf16_f32 v191, v182, v183
	v_cvt_pk_bf16_f32 v192, v184, v185
	v_cvt_pk_bf16_f32 v193, v186, v187
	global_store_dwordx4 v150, v[190:193], s[76:77]
	s_add_u32 s76, s76, 0x2000
	s_addc_u32 s77, s77, 0
	ds_read_b64 v[152:153], v148 offset:128
	ds_read_b128 v[154:157], v149 offset:10752
	ds_read_b128 v[158:161], v149 offset:10768
	ds_read_b128 v[162:165], v149 offset:10784
	ds_read_b128 v[166:169], v149 offset:10800
	s_waitcnt lgkmcnt(0)
	v_mul_f32_e32 v172, v153, v155
	v_fma_f32 v180, v152, v154, -v172
	v_mul_f32_e32 v174, v153, v157
	v_fma_f32 v181, v152, v156, -v174
	v_mul_f32_e32 v172, v153, v159
	v_fma_f32 v182, v152, v158, -v172
	v_mul_f32_e32 v174, v153, v161
	v_fma_f32 v183, v152, v160, -v174
	v_mul_f32_e32 v172, v153, v163
	v_fma_f32 v184, v152, v162, -v172
	v_mul_f32_e32 v174, v153, v165
	v_fma_f32 v185, v152, v164, -v174
	v_mul_f32_e32 v172, v153, v167
	v_fma_f32 v186, v152, v166, -v172
	v_mul_f32_e32 v174, v153, v169
	v_fma_f32 v187, v152, v168, -v174
	v_cvt_pk_bf16_f32 v190, v180, v181
	v_cvt_pk_bf16_f32 v191, v182, v183
	v_cvt_pk_bf16_f32 v192, v184, v185
	v_cvt_pk_bf16_f32 v193, v186, v187
	global_store_dwordx4 v150, v[190:193], s[76:77]
	s_add_u32 s76, s76, 0x2000
	s_addc_u32 s77, s77, 0
	ds_read_b64 v[152:153], v148 offset:256
	ds_read_b128 v[154:157], v149 offset:12800
	ds_read_b128 v[158:161], v149 offset:12816
	ds_read_b128 v[162:165], v149 offset:12832
	ds_read_b128 v[166:169], v149 offset:12848
	s_waitcnt lgkmcnt(0)
	v_mul_f32_e32 v172, v153, v155
	v_fma_f32 v180, v152, v154, -v172
	v_mul_f32_e32 v174, v153, v157
	v_fma_f32 v181, v152, v156, -v174
	v_mul_f32_e32 v172, v153, v159
	v_fma_f32 v182, v152, v158, -v172
	v_mul_f32_e32 v174, v153, v161
	v_fma_f32 v183, v152, v160, -v174
	v_mul_f32_e32 v172, v153, v163
	v_fma_f32 v184, v152, v162, -v172
	v_mul_f32_e32 v174, v153, v165
	v_fma_f32 v185, v152, v164, -v174
	v_mul_f32_e32 v172, v153, v167
	v_fma_f32 v186, v152, v166, -v172
	v_mul_f32_e32 v174, v153, v169
	v_fma_f32 v187, v152, v168, -v174
	v_cvt_pk_bf16_f32 v190, v180, v181
	v_cvt_pk_bf16_f32 v191, v182, v183
	v_cvt_pk_bf16_f32 v192, v184, v185
	v_cvt_pk_bf16_f32 v193, v186, v187
	global_store_dwordx4 v150, v[190:193], s[76:77]
	s_add_u32 s76, s76, 0x2000
	s_addc_u32 s77, s77, 0
	ds_read_b64 v[152:153], v148 offset:384
	ds_read_b128 v[154:157], v149 offset:14848
	ds_read_b128 v[158:161], v149 offset:14864
	ds_read_b128 v[162:165], v149 offset:14880
	ds_read_b128 v[166:169], v149 offset:14896
	s_waitcnt lgkmcnt(0)
	v_mul_f32_e32 v172, v153, v155
	v_fma_f32 v180, v152, v154, -v172
	v_mul_f32_e32 v174, v153, v157
	v_fma_f32 v181, v152, v156, -v174
	v_mul_f32_e32 v172, v153, v159
	v_fma_f32 v182, v152, v158, -v172
	v_mul_f32_e32 v174, v153, v161
	v_fma_f32 v183, v152, v160, -v174
	v_mul_f32_e32 v172, v153, v163
	v_fma_f32 v184, v152, v162, -v172
	v_mul_f32_e32 v174, v153, v165
	v_fma_f32 v185, v152, v164, -v174
	v_mul_f32_e32 v172, v153, v167
	v_fma_f32 v186, v152, v166, -v172
	v_mul_f32_e32 v174, v153, v169
	v_fma_f32 v187, v152, v168, -v174
	v_cvt_pk_bf16_f32 v190, v180, v181
	v_cvt_pk_bf16_f32 v191, v182, v183
	v_cvt_pk_bf16_f32 v192, v184, v185
	v_cvt_pk_bf16_f32 v193, v186, v187
	global_store_dwordx4 v150, v[190:193], s[76:77]
	s_add_u32 s76, s76, 0x2000
	s_addc_u32 s77, s77, 0
	ds_read_b64 v[152:153], v148 offset:0
	ds_read_b128 v[154:157], v149 offset:8704
	ds_read_b128 v[158:161], v149 offset:8720
	ds_read_b128 v[162:165], v149 offset:8736
	ds_read_b128 v[166:169], v149 offset:8752
	s_waitcnt lgkmcnt(0)
	v_mul_f32_e32 v172, v153, v154
	v_fma_f32 v180, v152, v155, v172
	v_mul_f32_e32 v174, v153, v156
	v_fma_f32 v181, v152, v157, v174
	v_mul_f32_e32 v172, v153, v158
	v_fma_f32 v182, v152, v159, v172
	v_mul_f32_e32 v174, v153, v160
	v_fma_f32 v183, v152, v161, v174
	v_mul_f32_e32 v172, v153, v162
	v_fma_f32 v184, v152, v163, v172
	v_mul_f32_e32 v174, v153, v164
	v_fma_f32 v185, v152, v165, v174
	v_mul_f32_e32 v172, v153, v166
	v_fma_f32 v186, v152, v167, v172
	v_mul_f32_e32 v174, v153, v168
	v_fma_f32 v187, v152, v169, v174
	v_cvt_pk_bf16_f32 v190, v180, v181
	v_cvt_pk_bf16_f32 v191, v182, v183
	v_cvt_pk_bf16_f32 v192, v184, v185
	v_cvt_pk_bf16_f32 v193, v186, v187
	global_store_dwordx4 v150, v[190:193], s[76:77]
	s_add_u32 s76, s76, 0x2000
	s_addc_u32 s77, s77, 0
	ds_read_b64 v[152:153], v148 offset:128
	ds_read_b128 v[154:157], v149 offset:10752
	ds_read_b128 v[158:161], v149 offset:10768
	ds_read_b128 v[162:165], v149 offset:10784
	ds_read_b128 v[166:169], v149 offset:10800
	s_waitcnt lgkmcnt(0)
; __device__ __forceinline__ unsigned pk2(float lo, float hi) { return f2bf(lo) | (f2bf(hi) << 16); }
; __global__ void __launch_bounds__(NWAVES * 64, 2) fwd_kernel(Args args) {
;     ...
;             for (int i2 = tid; i2 < 128 * 128; i2 += 512) { const int row = i2 >> 7, c0 = (i2 & 127) * 2, n = row & 63; float v[2];
; #pragma unroll
;                 for (int e = 0; e < 2; ++e) { const int col = c0 + e, tau = col >> 4, p = col & 15;
;                     const float ar = ap[((15 - tau) * 64 + n) * 2], ai = ap[((15 - tau) * 64 + n) * 2 + 1], br = bb[(n * 16 + p) * 2], bi = bb[(n * 16 + p) * 2 + 1];
;                     v[e] = (row < 64) ? (ar * br - ai * bi) : (ar * bi + ai * br); }
;                 *(unsigned*)(W1 + (size_t)row * 256 + c0) = pk2(v[0], v[1]); }
;             __syncthreads();
;         }
;     }
;     {
;         for (int i = gt; i < NTOK * 32; i += GT) { const int j = i & 31; const int p = pos_in[i >> 5];
;             const float inv = (float)exp2(-(double)j * (13.287712379549449 / 32.0));
	v_mul_f32_e32 v172, v153, v154
	v_fma_f32 v180, v152, v155, v172
	v_mul_f32_e32 v174, v153, v156
	v_fma_f32 v181, v152, v157, v174
	v_mul_f32_e32 v172, v153, v158
	v_fma_f32 v182, v152, v159, v172
	v_mul_f32_e32 v174, v153, v160
	v_fma_f32 v183, v152, v161, v174
	v_mul_f32_e32 v172, v153, v162
	v_fma_f32 v184, v152, v163, v172
	v_mul_f32_e32 v174, v153, v164
	v_fma_f32 v185, v152, v165, v174
	v_mul_f32_e32 v172, v153, v166
	v_fma_f32 v186, v152, v167, v172
	v_mul_f32_e32 v174, v153, v168
	v_fma_f32 v187, v152, v169, v174
	v_cvt_pk_bf16_f32 v190, v180, v181
	v_cvt_pk_bf16_f32 v191, v182, v183
	v_cvt_pk_bf16_f32 v192, v184, v185
	v_cvt_pk_bf16_f32 v193, v186, v187
	global_store_dwordx4 v150, v[190:193], s[76:77]
	s_add_u32 s76, s76, 0x2000
	s_addc_u32 s77, s77, 0
	ds_read_b64 v[152:153], v148 offset:256
	ds_read_b128 v[154:157], v149 offset:12800
	ds_read_b128 v[158:161], v149 offset:12816
	ds_read_b128 v[162:165], v149 offset:12832
	ds_read_b128 v[166:169], v149 offset:12848
	s_waitcnt lgkmcnt(0)
	v_mul_f32_e32 v172, v153, v154
	v_fma_f32 v180, v152, v155, v172
	v_mul_f32_e32 v174, v153, v156
	v_fma_f32 v181, v152, v157, v174
	v_mul_f32_e32 v172, v153, v158
	v_fma_f32 v182, v152, v159, v172
	v_mul_f32_e32 v174, v153, v160
	v_fma_f32 v183, v152, v161, v174
	v_mul_f32_e32 v172, v153, v162
	v_fma_f32 v184, v152, v163, v172
	v_mul_f32_e32 v174, v153, v164
	v_fma_f32 v185, v152, v165, v174
	v_mul_f32_e32 v172, v153, v166
	v_fma_f32 v186, v152, v167, v172
	v_mul_f32_e32 v174, v153, v168
	v_fma_f32 v187, v152, v169, v174
	v_cvt_pk_bf16_f32 v190, v180, v181
	v_cvt_pk_bf16_f32 v191, v182, v183
	v_cvt_pk_bf16_f32 v192, v184, v185
	v_cvt_pk_bf16_f32 v193, v186, v187
	global_store_dwordx4 v150, v[190:193], s[76:77]
	s_add_u32 s76, s76, 0x2000
	s_addc_u32 s77, s77, 0
	ds_read_b64 v[152:153], v148 offset:384
	ds_read_b128 v[154:157], v149 offset:14848
	ds_read_b128 v[158:161], v149 offset:14864
	ds_read_b128 v[162:165], v149 offset:14880
	ds_read_b128 v[166:169], v149 offset:14896
	s_waitcnt lgkmcnt(0)
	v_mul_f32_e32 v172, v153, v154
	v_fma_f32 v180, v152, v155, v172
	v_mul_f32_e32 v174, v153, v156
	v_fma_f32 v181, v152, v157, v174
	v_mul_f32_e32 v172, v153, v158
	v_fma_f32 v182, v152, v159, v172
	v_mul_f32_e32 v174, v153, v160
	v_fma_f32 v183, v152, v161, v174
	v_mul_f32_e32 v172, v153, v162
	v_fma_f32 v184, v152, v163, v172
	v_mul_f32_e32 v174, v153, v164
	v_fma_f32 v185, v152, v165, v174
	v_mul_f32_e32 v172, v153, v166
	v_fma_f32 v186, v152, v167, v172
	v_mul_f32_e32 v174, v153, v168
	v_fma_f32 v187, v152, v169, v174
	v_cvt_pk_bf16_f32 v190, v180, v181
	v_cvt_pk_bf16_f32 v191, v182, v183
	v_cvt_pk_bf16_f32 v192, v184, v185
	v_cvt_pk_bf16_f32 v193, v186, v187
	global_store_dwordx4 v150, v[190:193], s[76:77]
	s_add_u32 s76, s76, 0x2000
	s_addc_u32 s77, s77, 0
	s_or_b64 exec, exec, s[0:1]
	s_add_i32 s24, s24, s44
	s_add_i32 s68, s68, s44
	v_lshl_add_u64 v[2:3], v[2:3], 0, s[6:7]
	v_lshl_add_u64 v[4:5], v[4:5], 0, s[6:7]
	v_add_u32_e32 v23, s3, v23
	v_lshl_add_u64 v[6:7], v[6:7], 0, s[6:7]
	s_cmpk_gt_i32 s24, 0xff
	v_lshl_add_u64 v[8:9], v[8:9], 0, s[6:7]
	s_barrier
	s_cbranch_scc0 .LBB0_30
.LBB0_59:
	s_lshl_b32 s0, s2, 9
	v_writelane_b32 v255, s0, 3
	v_add_u32_e32 v4, s0, v38
	s_mov_b32 s0, 0x100000
	s_lshl_b32 s52, s44, 9
	v_cmp_gt_i32_e32 vcc, s0, v4
	v_and_b32_e32 v2, 31, v38
	s_and_saveexec_b64 s[4:5], vcc
	s_cbranch_execz .LBB0_62
	s_mov_b32 s0, 0x979a371
	v_cvt_f64_u32_e32 v[6:7], v2
	s_mov_b32 s1, 0xbfda934f
	v_mul_f64 v[6:7], v[6:7], s[0:1]
	v_rndne_f64_e32 v[8:9], v[6:7]
	s_mov_b32 s0, 0x3b39803f
	v_add_f64 v[10:11], v[6:7], -v[8:9]
	s_mov_b32 s1, 0x3c7abc9e
	v_mul_f64 v[12:13], v[10:11], s[0:1]
	s_mov_b32 s0, 0xfefa39ef
	s_mov_b32 s1, 0x3fe62e42
	v_fmac_f64_e32 v[12:13], s[0:1], v[10:11]
	s_mov_b32 s0, 0x6a5dcb37
	v_mov_b32_e32 v10, 0xfca7ab0c
	v_mov_b32_e32 v11, 0x3e928af3
	s_mov_b32 s1, 0x3e5ade15
	v_fmac_f64_e32 v[10:11], s[0:1], v[12:13]
	v_mov_b32_e32 v14, 0x623fde64
	v_mov_b32_e32 v15, 0x3ec71dee
	v_fmac_f64_e32 v[14:15], v[12:13], v[10:11]
	v_mov_b32_e32 v10, 0x7c89e6b0
	v_mov_b32_e32 v11, 0x3efa0199
	v_fmac_f64_e32 v[10:11], v[12:13], v[14:15]
	v_mov_b32_e32 v14, 0x14761f6e
	v_mov_b32_e32 v15, 0x3f2a01a0
	v_fmac_f64_e32 v[14:15], v[12:13], v[10:11]
	v_mov_b32_e32 v10, 0x1852b7b0
	v_mov_b32_e32 v11, 0x3f56c16c
	v_fmac_f64_e32 v[10:11], v[12:13], v[14:15]
	v_mov_b32_e32 v14, 0x11122322
	v_mov_b32_e32 v15, 0x3f811111
	v_fmac_f64_e32 v[14:15], v[12:13], v[10:11]
	v_mov_b32_e32 v10, 0x555502a1
	v_mov_b32_e32 v11, 0x3fa55555
	v_fmac_f64_e32 v[10:11], v[12:13], v[14:15]
	v_mov_b32_e32 v14, 0x55555511
	v_mov_b32_e32 v15, 0x3fc55555
	v_fmac_f64_e32 v[14:15], v[12:13], v[10:11]
	v_mov_b32_e32 v10, 11
	v_mov_b32_e32 v11, 0x3fe00000
	s_mov_b32 s0, 0
	v_fmac_f64_e32 v[10:11], v[12:13], v[14:15]
	s_mov_b32 s1, 0x40900000
	v_fma_f64 v[10:11], v[12:13], v[10:11], 1.0
	v_cmp_nlt_f64_e32 vcc, s[0:1], v[6:7]
	s_mov_b32 s0, 0
	v_fma_f64 v[10:11], v[12:13], v[10:11], 1.0
	v_cvt_i32_f64_e32 v1, v[8:9]
	s_mov_b32 s1, 0xc090cc00
	v_ldexp_f64 v[8:9], v[10:11], v1
	v_mov_b32_e32 v1, 0x7ff00000
	v_cmp_ngt_f64_e64 s[0:1], s[0:1], v[6:7]
	v_cndmask_b32_e32 v1, v1, v9, vcc
	s_and_b64 vcc, s[0:1], vcc
	v_cndmask_b32_e64 v7, 0, v1, s[0:1]
	v_cndmask_b32_e32 v6, 0, v8, vcc
	v_ashrrev_i32_e32 v5, 31, v4
	v_cvt_f32_f64_e32 v1, v[6:7]
	v_lshl_add_u64 v[6:7], v[4:5], 2, s[46:47]
	s_mov_b64 s[0:1], 0x500000
	s_ashr_i32 s53, s52, 31
	s_mov_b32 s12, 0x6dc9c883
	v_lshl_add_u64 v[6:7], v[6:7], 0, s[0:1]
	s_lshl_b64 s[0:1], s[52:53], 2
	s_mov_b64 s[6:7], 0
	s_mov_b32 s13, 0x3fc45f30
	s_mov_b32 s3, 0xfffff
	s_mov_b64 s[74:75], exec
	s_mov_b32 s73, 0x100000
	s_add_u32 s94, s46, 0x100000
	s_addc_u32 s95, s47, 0
	s_add_u32 s96, s46, 0x500000
	s_addc_u32 s97, s47, 0
; __device__ __forceinline__ void sincos_d(double ang, float& s, float& c) { double t = ang * 0.15915494309189535; t -= rint(t); const float f = (float)t; s = __builtin_amdgcn_sinf(f); c = __builtin_amdgcn_cosf(f); }
; __global__ void __launch_bounds__(NWAVES * 64, 2) fwd_kernel(Args args) {
;     ...
;     {
;         for (int i = gt; i < NTOK * 32; i += GT) { const int j = i & 31; const int p = pos_in[i >> 5];
;             const float inv = (float)exp2(-(double)j * (13.287712379549449 / 32.0));
;             const float ang = (float)p * inv; float s, c; sincos_d((double)ang, s, c);
;             ROPEC[i] = c; ROPES[i] = s; }
;     }
.Lxs_rope_chunk:
	s_mov_b32 s72, 0
	v_add_u32_e32 v150, s72, v4
	v_cmp_gt_u32_e64 s[76:77], s73, v150
	v_ashrrev_i32_e32 v160, 5, v150
	v_lshlrev_b32_e32 v160, 2, v160
	s_and_b64 s[76:77], s[76:77], s[74:75]
	s_mov_b64 exec, s[76:77]
	global_load_dword v170, v160, s[30:31]
	s_add_i32 s72, s72, s52
	v_add_u32_e32 v151, s72, v4
	v_cmp_gt_u32_e64 s[78:79], s73, v151
	v_ashrrev_i32_e32 v161, 5, v151
	v_lshlrev_b32_e32 v161, 2, v161
	s_and_b64 s[78:79], s[78:79], s[74:75]
	s_mov_b64 exec, s[78:79]
	global_load_dword v171, v161, s[30:31]
	s_add_i32 s72, s72, s52
	v_add_u32_e32 v152, s72, v4
	v_cmp_gt_u32_e64 s[80:81], s73, v152
	v_ashrrev_i32_e32 v162, 5, v152
	v_lshlrev_b32_e32 v162, 2, v162
	s_and_b64 s[80:81], s[80:81], s[74:75]
	s_mov_b64 exec, s[80:81]
	global_load_dword v172, v162, s[30:31]
	s_add_i32 s72, s72, s52
	v_add_u32_e32 v153, s72, v4
	v_cmp_gt_u32_e64 s[82:83], s73, v153
	v_ashrrev_i32_e32 v163, 5, v153
	v_lshlrev_b32_e32 v163, 2, v163
	s_and_b64 s[82:83], s[82:83], s[74:75]
	s_mov_b64 exec, s[82:83]
	global_load_dword v173, v163, s[30:31]
	s_add_i32 s72, s72, s52
	v_add_u32_e32 v154, s72, v4
	v_cmp_gt_u32_e64 s[84:85], s73, v154
	v_ashrrev_i32_e32 v164, 5, v154
	v_lshlrev_b32_e32 v164, 2, v164
	s_and_b64 s[84:85], s[84:85], s[74:75]
	s_mov_b64 exec, s[84:85]
	global_load_dword v174, v164, s[30:31]
	s_add_i32 s72, s72, s52
	v_add_u32_e32 v155, s72, v4
	v_cmp_gt_u32_e64 s[86:87], s73, v155
	v_ashrrev_i32_e32 v165, 5, v155
	v_lshlrev_b32_e32 v165, 2, v165
	s_and_b64 s[86:87], s[86:87], s[74:75]
	s_mov_b64 exec, s[86:87]
	global_load_dword v175, v165, s[30:31]
	s_add_i32 s72, s72, s52
	v_add_u32_e32 v156, s72, v4
	v_cmp_gt_u32_e64 s[88:89], s73, v156
	v_ashrrev_i32_e32 v166, 5, v156
	v_lshlrev_b32_e32 v166, 2, v166
	s_and_b64 s[88:89], s[88:89], s[74:75]
	s_mov_b64 exec, s[88:89]
	global_load_dword v176, v166, s[30:31]
	s_add_i32 s72, s72, s52
	v_add_u32_e32 v157, s72, v4
	v_cmp_gt_u32_e64 s[90:91], s73, v157
	v_ashrrev_i32_e32 v167, 5, v157
	v_lshlrev_b32_e32 v167, 2, v167
	s_and_b64 s[90:91], s[90:91], s[74:75]
	s_mov_b64 exec, s[90:91]
	global_load_dword v177, v167, s[30:31]
	s_add_i32 s72, s72, s52
	s_mov_b64 exec, s[74:75]
	s_waitcnt vmcnt(0)
	s_mov_b64 exec, s[76:77]
	v_cvt_f32_i32_e32 v180, v170
	v_mul_f32_e32 v180, v1, v180
	v_cvt_f64_f32_e32 v[182:183], v180
	v_mul_f64 v[184:185], v[182:183], s[12:13]
	v_rndne_f64_e32 v[184:185], v[184:185]
	v_fma_f64 v[182:183], v[182:183], s[12:13], -v[184:185]
	v_cvt_f32_f64_e32 v180, v[182:183]
	v_cos_f32_e32 v186, v180
	v_sin_f32_e32 v187, v180
	v_lshlrev_b32_e32 v188, 2, v150
	global_store_dword v188, v186, s[94:95]
	global_store_dword v188, v187, s[96:97]
	s_mov_b64 exec, s[78:79]
	v_cvt_f32_i32_e32 v180, v171
	v_mul_f32_e32 v180, v1, v180
	v_cvt_f64_f32_e32 v[182:183], v180
	v_mul_f64 v[184:185], v[182:183], s[12:13]
	v_rndne_f64_e32 v[184:185], v[184:185]
	v_fma_f64 v[182:183], v[182:183], s[12:13], -v[184:185]
	v_cvt_f32_f64_e32 v180, v[182:183]
	v_cos_f32_e32 v186, v180
	v_sin_f32_e32 v187, v180
	v_lshlrev_b32_e32 v188, 2, v151
	global_store_dword v188, v186, s[94:95]
	global_store_dword v188, v187, s[96:97]
	s_mov_b64 exec, s[80:81]
	v_cvt_f32_i32_e32 v180, v172
	v_mul_f32_e32 v180, v1, v180
	v_cvt_f64_f32_e32 v[182:183], v180
	v_mul_f64 v[184:185], v[182:183], s[12:13]
	v_rndne_f64_e32 v[184:185], v[184:185]
	v_fma_f64 v[182:183], v[182:183], s[12:13], -v[184:185]
	v_cvt_f32_f64_e32 v180, v[182:183]
	v_cos_f32_e32 v186, v180
	v_sin_f32_e32 v187, v180
	v_lshlrev_b32_e32 v188, 2, v152
	global_store_dword v188, v186, s[94:95]
	global_store_dword v188, v187, s[96:97]
	s_mov_b64 exec, s[82:83]
	v_cvt_f32_i32_e32 v180, v173
	v_mul_f32_e32 v180, v1, v180
	v_cvt_f64_f32_e32 v[182:183], v180
	v_mul_f64 v[184:185], v[182:183], s[12:13]
	v_rndne_f64_e32 v[184:185], v[184:185]
	v_fma_f64 v[182:183], v[182:183], s[12:13], -v[184:185]
	v_cvt_f32_f64_e32 v180, v[182:183]
	v_cos_f32_e32 v186, v180
	v_sin_f32_e32 v187, v180
	v_lshlrev_b32_e32 v188, 2, v153
	global_store_dword v188, v186, s[94:95]
	global_store_dword v188, v187, s[96:97]
	s_mov_b64 exec, s[84:85]
	v_cvt_f32_i32_e32 v180, v174
	v_mul_f32_e32 v180, v1, v180
	v_cvt_f64_f32_e32 v[182:183], v180
	v_mul_f64 v[184:185], v[182:183], s[12:13]
	v_rndne_f64_e32 v[184:185], v[184:185]
	v_fma_f64 v[182:183], v[182:183], s[12:13], -v[184:185]
	v_cvt_f32_f64_e32 v180, v[182:183]
	v_cos_f32_e32 v186, v180
	v_sin_f32_e32 v187, v180
	v_lshlrev_b32_e32 v188, 2, v154
	global_store_dword v188, v186, s[94:95]
	global_store_dword v188, v187, s[96:97]
	s_mov_b64 exec, s[86:87]
	v_cvt_f32_i32_e32 v180, v175
	v_mul_f32_e32 v180, v1, v180
	v_cvt_f64_f32_e32 v[182:183], v180
	v_mul_f64 v[184:185], v[182:183], s[12:13]
	v_rndne_f64_e32 v[184:185], v[184:185]
	v_fma_f64 v[182:183], v[182:183], s[12:13], -v[184:185]
	v_cvt_f32_f64_e32 v180, v[182:183]
	v_cos_f32_e32 v186, v180
	v_sin_f32_e32 v187, v180
	v_lshlrev_b32_e32 v188, 2, v155
	global_store_dword v188, v186, s[94:95]
	global_store_dword v188, v187, s[96:97]
	s_mov_b64 exec, s[88:89]
	v_cvt_f32_i32_e32 v180, v176
	v_mul_f32_e32 v180, v1, v180
	v_cvt_f64_f32_e32 v[182:183], v180
	v_mul_f64 v[184:185], v[182:183], s[12:13]
	v_rndne_f64_e32 v[184:185], v[184:185]
	v_fma_f64 v[182:183], v[182:183], s[12:13], -v[184:185]
	v_cvt_f32_f64_e32 v180, v[182:183]
	v_cos_f32_e32 v186, v180
	v_sin_f32_e32 v187, v180
	v_lshlrev_b32_e32 v188, 2, v156
	global_store_dword v188, v186, s[94:95]
	global_store_dword v188, v187, s[96:97]
	s_mov_b64 exec, s[90:91]
	v_cvt_f32_i32_e32 v180, v177
	v_mul_f32_e32 v180, v1, v180
	v_cvt_f64_f32_e32 v[182:183], v180
	v_mul_f64 v[184:185], v[182:183], s[12:13]
	v_rndne_f64_e32 v[184:185], v[184:185]
	v_fma_f64 v[182:183], v[182:183], s[12:13], -v[184:185]
	v_cvt_f32_f64_e32 v180, v[182:183]
	v_cos_f32_e32 v186, v180
	v_sin_f32_e32 v187, v180
	v_lshlrev_b32_e32 v188, 2, v157
	global_store_dword v188, v186, s[94:95]
	global_store_dword v188, v187, s[96:97]
	s_mov_b64 exec, s[74:75]
	s_lshl_b32 s72, s52, 3
	v_add_u32_e32 v4, s72, v4
	v_cmp_gt_u32_e32 vcc, s73, v4
	s_and_b64 s[74:75], s[74:75], vcc
	s_mov_b64 exec, s[74:75]
	s_cbranch_execnz .Lxs_rope_chunk
